# in-proj epilogue row scales: dead denormal rescue around v_rsq_f32 removed (x >= 1e-6), bit-exact
# speedup vs baseline: 1.0091x; 1.0091x over previous
.LBB0_269:
	s_lshl_b32 s23, s42, 8
	s_add_i32 s23, s23, s80
	v_or_b32_e32 v174, s23, v145
	v_ashrrev_i32_e32 v175, 31, v174
	s_mov_b32 s100, 0x20000
	v_and_b32_e32 v128, 0xff, v174
	v_lshl_add_u32 v128, v128, 2, s100
	ds_read_b32 v130, v128
	ds_read_b32 v131, v128 offset:64
	ds_read_b32 v132, v128 offset:128
	ds_read_b32 v133, v128 offset:192
	ds_read_b32 v134, v128 offset:512
	ds_read_b32 v135, v128 offset:576
	ds_read_b32 v156, v128 offset:640
	s_nop 0
	ds_read_b32 v128, v128 offset:704
	v_add_u32_e32 v164, 0x80, v174
	v_ashrrev_i32_e32 v165, 31, v164
	s_mov_b64 s[30:31], -1
	s_cmp_lg_u32 s49, 15
	s_waitcnt lgkmcnt(0)
	v_fmamk_f32 v129, v130, 0x3a800000, v192
	v_fmamk_f32 v128, v128, 0x3a800000, v192
	v_rsq_f32_e32 v129, v129
	s_nop 0
	v_mov_b32_e32 v172, v129
	v_fmamk_f32 v129, v131, 0x3a800000, v192
	s_nop 0
	v_rsq_f32_e32 v129, v129
	s_nop 0
	v_mov_b32_e32 v170, v129
	v_fmamk_f32 v129, v132, 0x3a800000, v192
	s_nop 0
	v_rsq_f32_e32 v129, v129
	s_nop 0
	v_mov_b32_e32 v168, v129
	v_fmamk_f32 v129, v133, 0x3a800000, v192
	s_nop 0
	v_rsq_f32_e32 v129, v129
	s_nop 0
	v_mov_b32_e32 v166, v129
	v_fmamk_f32 v129, v134, 0x3a800000, v192
	s_nop 0
	v_rsq_f32_e32 v129, v129
	s_nop 0
	v_mov_b32_e32 v162, v129
	v_fmamk_f32 v129, v135, 0x3a800000, v192
	s_nop 0
	v_rsq_f32_e32 v129, v129
	s_nop 0
	v_mov_b32_e32 v160, v129
	v_fmamk_f32 v129, v156, 0x3a800000, v192
	s_nop 0
	v_rsq_f32_e32 v129, v129
	s_nop 0
	v_mov_b32_e32 v158, v129
	v_cmp_gt_f32_e32 vcc, s93, v128
	v_mul_f32_e32 v129, 0x4b800000, v128
	s_nop 0
	v_cndmask_b32_e32 v128, v128, v129, vcc
	v_rsq_f32_e32 v128, v128
	s_nop 0
	v_mul_f32_e32 v129, 0x45800000, v128
	v_cndmask_b32_e32 v156, v128, v129, vcc
	s_cbranch_scc1 .LBB0_272
	s_and_b64 vcc, exec, s[30:31]
	s_cbranch_vccnz .LBB0_477
